# phase 4a: blocks >=256 run the GLU GEMM first and rwkv_post second (co-resident blocks overlap memory-bound and compute-bound passes)
# baseline (speedup 1.0000x reference)
.LBB0_635:
	s_or_b64 exec, exec, s[10:11]
	s_waitcnt lgkmcnt(0)
	s_barrier
	s_mov_b32 s98, 0
	s_cmp_lt_u32 s33, 0x200
	s_cbranch_scc1 .Lmy_p4a_norm
	s_cmp_lt_u32 s2, 0x100
	s_cbranch_scc1 .Lmy_p4a_norm
	s_mov_b32 s98, 1
	s_mov_b64 s[100:101], s[78:79]
	v_mov_b32_e32 v239, v110
	s_branch .LBB0_644
.Lmy_p4a_norm:
	s_cmpk_gt_i32 s2, 0x21ff
	s_cbranch_scc1 .LBB0_644
.Lmy_p4a_post:
	v_bfe_u32 v13, v100, 4, 3
	v_lshl_or_b32 v12, v13, 6, v110
	v_readlane_b32 s36, v238, 0
	v_lshlrev_b32_e32 v14, 2, v12
	v_readlane_b32 s37, v238, 1
	v_readlane_b32 s38, v238, 2
	v_readlane_b32 s39, v238, 3
	v_readlane_b32 s40, v238, 4
	v_readlane_b32 s41, v238, 5
	v_readlane_b32 s42, v238, 6
	v_readlane_b32 s43, v238, 7
	v_readlane_b32 s44, v238, 8
	v_readlane_b32 s45, v238, 9
	v_readlane_b32 s46, v238, 10
	v_readlane_b32 s47, v238, 11
	v_readlane_b32 s48, v238, 12
	v_readlane_b32 s49, v238, 13
	v_readlane_b32 s50, v238, 14
	v_readlane_b32 s51, v238, 15
	global_load_dwordx4 v[0:3], v14, s[40:41]
	global_load_dwordx4 v[4:7], v14, s[38:39]
	v_readlane_b32 s36, v236, 48
	v_mov_b32_e32 v15, 0
	v_readlane_b32 s37, v236, 49
	v_readlane_b32 s44, v236, 56
	v_readlane_b32 s45, v236, 57
	v_lshl_add_u64 v[8:9], s[36:37], 0, v[14:15]
	v_add_co_u32_e32 v8, vcc, 0x1000, v8
	v_readlane_b32 s46, v236, 58
	s_nop 0
	v_addc_co_u32_e32 v9, vcc, 0, v9, vcc
	global_load_dwordx4 v[8:11], v[8:9], off
	v_readlane_b32 s47, v236, 59
	v_readlane_b32 s48, v236, 60
	v_readlane_b32 s49, v236, 61
	v_readlane_b32 s50, v236, 62
	v_readlane_b32 s51, v236, 63
	v_readlane_b32 s44, v238, 48
	v_readlane_b32 s38, v236, 50
	v_readlane_b32 s39, v236, 51
	v_readlane_b32 s40, v236, 52
	v_readlane_b32 s41, v236, 53
	v_readlane_b32 s42, v236, 54
	v_readlane_b32 s43, v236, 55
	v_lshlrev_b32_e32 v18, 2, v13
	v_mov_b32_e32 v19, v15
	v_readlane_b32 s45, v238, 49
	v_readlane_b32 s46, v238, 50
	v_readlane_b32 s47, v238, 51
	v_readlane_b32 s48, v238, 52
	v_readlane_b32 s49, v238, 53
	v_readlane_b32 s50, v238, 54
	v_readlane_b32 s51, v238, 55
	v_lshl_add_u64 v[18:19], s[48:49], 0, v[18:19]
	v_readlane_b32 s36, v238, 32
	v_readlane_b32 s37, v238, 33
	v_readlane_b32 s44, v238, 40
	v_readlane_b32 s45, v238, 41
	v_readlane_b32 s38, v238, 34
	v_readlane_b32 s39, v238, 35
	v_readlane_b32 s40, v238, 36
	v_readlane_b32 s41, v238, 37
	v_readlane_b32 s42, v238, 38
	v_readlane_b32 s43, v238, 39
	v_readlane_b32 s46, v238, 42
	v_readlane_b32 s47, v238, 43
	v_readlane_b32 s48, v238, 44
	v_readlane_b32 s49, v238, 45
	v_readlane_b32 s50, v238, 46
	v_readlane_b32 s51, v238, 47
	s_mov_b64 s[24:25], s[44:45]
	s_mov_b64 s[16:17], s[36:37]
	s_mov_b64 s[26:27], s[46:47]
	s_mov_b64 s[28:29], s[48:49]
	s_mov_b64 s[30:31], s[50:51]
	s_mov_b64 s[18:19], s[38:39]
	v_readlane_b32 s36, v238, 16
	v_mov_b32_e32 v27, v15
	v_readlane_b32 s54, v238, 58
	v_readlane_b32 s55, v238, 59
	v_lshlrev_b32_e32 v26, 1, v12
	v_readlane_b32 s38, v238, 18
	v_readlane_b32 s39, v238, 19
	v_lshl_add_u32 v16, s2, 1, v150
	s_lshl_b32 s0, s33, 1
	s_movk_i32 s1, 0x3fff
	s_movk_i32 s3, 0x4000
	v_mov_b32_e32 v34, 0x7ff
	s_movk_i32 s14, 0x1200
	s_movk_i32 s15, 0x1c00
	v_mov_b32_e32 v35, 0x3a27c5ac
	s_mov_b32 s20, 0x800000
	s_movk_i32 s21, 0x7fff
	v_mov_b32_e32 v36, 1
	v_lshl_add_u64 v[20:21], s[24:25], 0, v[26:27]
	v_lshl_add_u64 v[22:23], s[16:17], 0, v[26:27]
	v_lshl_add_u64 v[24:25], s[38:39], 0, v[14:15]
	v_lshl_add_u64 v[26:27], s[54:55], 0, v[26:27]
	v_lshlrev_b32_e32 v14, 2, v12
	s_waitcnt vmcnt(2)
	v_mov_b32_e32 v28, v1
	v_mov_b32_e32 v29, v3
	s_waitcnt vmcnt(1)
	v_mov_b32_e32 v30, v5
	v_mov_b32_e32 v31, v7
	v_mov_b32_e32 v1, v2
	v_mov_b32_e32 v5, v6
	s_mov_b32 s16, s2
	v_readlane_b32 s52, v238, 56
	v_readlane_b32 s53, v238, 57
	v_readlane_b32 s56, v238, 60
	v_readlane_b32 s57, v238, 61
	v_readlane_b32 s58, v238, 62
	s_waitcnt vmcnt(0)
	v_mov_b32_e32 v2, v9
	v_mov_b32_e32 v3, v11
	v_mov_b32_e32 v9, v10
	v_readlane_b32 s59, v238, 63
	v_readlane_b32 s37, v238, 17
	v_readlane_b32 s40, v238, 20
	v_readlane_b32 s41, v238, 21
	v_readlane_b32 s42, v238, 22
	v_readlane_b32 s43, v238, 23
	v_readlane_b32 s44, v238, 24
	v_readlane_b32 s45, v238, 25
	v_readlane_b32 s46, v238, 26
	v_readlane_b32 s47, v238, 27
	v_readlane_b32 s48, v238, 28
	v_readlane_b32 s49, v238, 29
	v_readlane_b32 s50, v238, 30
	v_readlane_b32 s51, v238, 31
	s_branch .LBB0_639

.LBB0_644:
	v_readlane_b32 s72, v238, 16
	v_readlane_b32 s40, v238, 48
	s_cmpk_gt_i32 s2, 0x23f
	v_lshlrev_b32_e32 v78, 2, v151
	v_readlane_b32 s73, v238, 17
	v_readlane_b32 s74, v238, 18
	v_readlane_b32 s75, v238, 19
	v_readlane_b32 s76, v238, 20
	v_readlane_b32 s77, v238, 21
	v_readlane_b32 s78, v238, 22
	v_readlane_b32 s79, v238, 23
	v_readlane_b32 s80, v238, 24
	v_readlane_b32 s81, v238, 25
	v_readlane_b32 s82, v238, 26
	v_readlane_b32 s83, v238, 27
	v_readlane_b32 s86, v238, 30
	v_readlane_b32 s87, v238, 31
	v_readlane_b32 s41, v238, 49
	v_readlane_b32 s42, v238, 50
	v_readlane_b32 s43, v238, 51
	v_readlane_b32 s50, v238, 58
	v_readlane_b32 s51, v238, 59
	v_readlane_b32 s84, v238, 28
	v_readlane_b32 s85, v238, 29
	v_readlane_b32 s44, v238, 52
	v_readlane_b32 s45, v238, 53
	v_readlane_b32 s46, v238, 54
	v_readlane_b32 s47, v238, 55
	v_readlane_b32 s48, v238, 56
	v_readlane_b32 s49, v238, 57
	v_readlane_b32 s52, v238, 60
	v_readlane_b32 s53, v238, 61
	v_readlane_b32 s54, v238, 62
	v_readlane_b32 s55, v238, 63
	s_cbranch_scc1 .LBB0_669
	s_cmp_eq_u32 s98, 2
	s_cbranch_scc1 .LBB0_669
	v_readlane_b32 s12, v238, 32
	v_and_b32_e32 v0, 32, v153
	v_readlane_b32 s18, v238, 38
	v_readlane_b32 s19, v238, 39
	v_readlane_b32 s22, v238, 42
	v_readlane_b32 s23, v238, 43
	v_lshlrev_b32_e32 v64, 1, v0
	v_lshlrev_b32_e32 v66, 2, v0
	v_mov_b32_e32 v67, 0
	s_mov_b64 s[18:19], s[22:23]
	v_readlane_b32 s52, v236, 0
	v_and_b32_e32 v0, 1, v100
	v_and_b32_e32 v1, 0xe0, v97
	v_lshl_add_u64 v[68:69], s[18:19], 0, v[66:67]
	v_mov_b32_e32 v65, v67
	v_readlane_b32 s54, v236, 2
	v_readlane_b32 s55, v236, 3
	v_lshlrev_b32_e32 v66, 7, v0
	v_add_u32_e32 v0, 0x300, v100
	v_or_b32_e32 v2, v1, v101
	v_and_b32_e32 v3, 0x1c0, v105
	v_lshl_add_u64 v[70:71], s[54:55], 0, v[64:65]
	v_lshrrev_b32_e32 v65, 5, v0
	v_add_u32_e32 v0, 0x200, v100
	s_movk_i32 s0, 0x90
	v_mul_u32_u24_e32 v80, 0x90, v2
	v_and_b32_e32 v2, 0x5f, v100
	v_or_b32_e32 v4, v3, v101
	v_lshrrev_b32_e32 v88, 5, v0
	v_add_u32_e32 v0, 0x100, v100
	v_mul_u32_u24_e32 v81, 0x90, v2
	v_or_b32_e32 v1, v78, v1
	v_mul_u32_u24_e32 v4, 0x90, v4
	v_or_b32_e32 v3, v78, v3
	v_mad_u32_u24 v83, v105, s0, v64
	v_lshlrev_b32_e32 v2, 2, v2
	s_movk_i32 s3, 0x210
	v_readlane_b32 s21, v238, 41
	s_lshl_b32 s0, s2, 4
	v_lshrrev_b32_e32 v91, 5, v0
	v_mul_u32_u24_e32 v79, 0x90, v105
	v_and_b32_e32 v82, 0x7c, v149
	v_mad_u32_u24 v84, v1, s3, v2
	v_mad_u32_u24 v85, v3, s3, v2
	v_lshl_add_u64 v[72:73], s[18:19], 0, v[66:67]
	v_mad_u32_u24 v86, v65, s3, v98
	v_or_b32_e32 v87, 0x4000, v65
	s_add_i32 s0, s0, 0x7fffe000
	s_lshl_b32 s1, s33, 4
	v_mad_u32_u24 v89, v88, s3, v98
	v_or_b32_e32 v90, 0x4000, v88
	v_mad_u32_u24 v92, v91, s3, v98
	v_or_b32_e32 v93, 0x4000, v91
	v_mad_u32_u24 v94, v147, s3, v98
	v_or_b32_e32 v95, 0x4000, v147
	s_movk_i32 s3, 0x7fff
	s_mov_b32 s21, 0
	v_add_u32_e32 v109, v148, v4
	v_mov_b32_e32 v110, 1
	s_mov_b32 s22, s2
	v_readlane_b32 s13, v238, 33
	v_readlane_b32 s14, v238, 34
	v_readlane_b32 s15, v238, 35
	v_readlane_b32 s16, v238, 36
	v_readlane_b32 s17, v238, 37
	v_readlane_b32 s20, v238, 40
	v_readlane_b32 s24, v238, 44
	v_readlane_b32 s25, v238, 45
	v_readlane_b32 s26, v238, 46
	v_readlane_b32 s27, v238, 47
	v_readlane_b32 s53, v236, 1
	v_readlane_b32 s56, v236, 4
	v_readlane_b32 s57, v236, 5
	v_readlane_b32 s58, v236, 6
	v_readlane_b32 s59, v236, 7
	s_branch .LBB0_647

.LBB0_669:
	s_cmp_eq_u32 s98, 1
	s_cbranch_scc0 .Lmy_p4a_end
	s_mov_b32 s98, 2
	s_mov_b64 s[78:79], s[100:101]
	v_mov_b32_e32 v110, v239
	s_branch .Lmy_p4a_post
